# P5 epilogue re-written, scalar v_mul instead of v_pk_mul
# speedup vs baseline: 1.0028x; 1.0015x over previous
.LBB0_510:
	s_lshl_b32 s17, s24, 7
	s_lshl_b32 s21, s25, 2
	s_add_i32 s17, s17, s21
	s_or_b32 s24, s17, s50
	s_ashr_i32 s25, s24, 31
	s_lshl_b64 s[24:25], s[24:25], 15
	s_add_u32 s24, s70, s24
	s_addc_u32 s25, s71, s25
	v_add_u32_e32 v166, s8, v136
	v_add_u32_e32 v166, v166, v160
	v_max_f32_e32 v124, 0, v124
	v_max_f32_e32 v125, 0, v125
	v_max_f32_e32 v126, 0, v126
	v_max_f32_e32 v127, 0, v127
	v_max_f32_e32 v120, 0, v120
	v_max_f32_e32 v121, 0, v121
	v_max_f32_e32 v122, 0, v122
	v_max_f32_e32 v123, 0, v123
	v_mul_f32_e32 v124, v124, v124
	v_mul_f32_e32 v125, v125, v125
	v_mul_f32_e32 v126, v126, v126
	v_mul_f32_e32 v127, v127, v127
	v_mul_f32_e32 v120, v120, v120
	v_mul_f32_e32 v121, v121, v121
	v_mul_f32_e32 v122, v122, v122
	v_mul_f32_e32 v123, v123, v123
	v_cvt_pk_bf16_f32 v124, v124, v125
	v_cvt_pk_bf16_f32 v125, v126, v127
	v_cvt_pk_bf16_f32 v126, v120, v121
	v_cvt_pk_bf16_f32 v127, v122, v123
	s_mov_b32 s98, s24
	s_mov_b32 s99, s25
	s_nop 0
	global_store_dwordx4 v166, v[124:127], s[98:99]
	v_max_f32_e32 v116, 0, v116
	v_max_f32_e32 v117, 0, v117
	v_max_f32_e32 v118, 0, v118
	v_max_f32_e32 v119, 0, v119
	v_max_f32_e32 v112, 0, v112
	v_max_f32_e32 v113, 0, v113
	v_max_f32_e32 v114, 0, v114
	v_max_f32_e32 v115, 0, v115
	v_mul_f32_e32 v116, v116, v116
	v_mul_f32_e32 v117, v117, v117
	v_mul_f32_e32 v118, v118, v118
	v_mul_f32_e32 v119, v119, v119
	v_mul_f32_e32 v112, v112, v112
	v_mul_f32_e32 v113, v113, v113
	v_mul_f32_e32 v114, v114, v114
	v_mul_f32_e32 v115, v115, v115
	v_cvt_pk_bf16_f32 v116, v116, v117
	v_cvt_pk_bf16_f32 v117, v118, v119
	v_cvt_pk_bf16_f32 v118, v112, v113
	v_cvt_pk_bf16_f32 v119, v114, v115
	s_add_u32 s98, s24, 0x10000
	s_addc_u32 s99, s25, 0
	s_nop 0
	global_store_dwordx4 v166, v[116:119], s[98:99]
	v_max_f32_e32 v108, 0, v108
	v_max_f32_e32 v109, 0, v109
	v_max_f32_e32 v110, 0, v110
	v_max_f32_e32 v111, 0, v111
	v_max_f32_e32 v104, 0, v104
	v_max_f32_e32 v105, 0, v105
	v_max_f32_e32 v106, 0, v106
	v_max_f32_e32 v107, 0, v107
	v_mul_f32_e32 v108, v108, v108
	v_mul_f32_e32 v109, v109, v109
	v_mul_f32_e32 v110, v110, v110
	v_mul_f32_e32 v111, v111, v111
	v_mul_f32_e32 v104, v104, v104
	v_mul_f32_e32 v105, v105, v105
	v_mul_f32_e32 v106, v106, v106
	v_mul_f32_e32 v107, v107, v107
	v_cvt_pk_bf16_f32 v108, v108, v109
	v_cvt_pk_bf16_f32 v109, v110, v111
	v_cvt_pk_bf16_f32 v110, v104, v105
	v_cvt_pk_bf16_f32 v111, v106, v107
	s_add_u32 s98, s24, 0x800
	s_addc_u32 s99, s25, 0
	s_nop 0
	global_store_dwordx4 v166, v[108:111], s[98:99]
	v_max_f32_e32 v100, 0, v100
	v_max_f32_e32 v101, 0, v101
	v_max_f32_e32 v102, 0, v102
	v_max_f32_e32 v103, 0, v103
	v_max_f32_e32 v96, 0, v96
	v_max_f32_e32 v97, 0, v97
	v_max_f32_e32 v98, 0, v98
	v_max_f32_e32 v99, 0, v99
	v_mul_f32_e32 v100, v100, v100
	v_mul_f32_e32 v101, v101, v101
	v_mul_f32_e32 v102, v102, v102
	v_mul_f32_e32 v103, v103, v103
	v_mul_f32_e32 v96, v96, v96
	v_mul_f32_e32 v97, v97, v97
	v_mul_f32_e32 v98, v98, v98
	v_mul_f32_e32 v99, v99, v99
	v_cvt_pk_bf16_f32 v100, v100, v101
	v_cvt_pk_bf16_f32 v101, v102, v103
	v_cvt_pk_bf16_f32 v102, v96, v97
	v_cvt_pk_bf16_f32 v103, v98, v99
	s_add_u32 s98, s24, 0x10800
	s_addc_u32 s99, s25, 0
	s_nop 0
	global_store_dwordx4 v166, v[100:103], s[98:99]
	v_max_f32_e32 v92, 0, v92
	v_max_f32_e32 v93, 0, v93
	v_max_f32_e32 v94, 0, v94
	v_max_f32_e32 v95, 0, v95
	v_max_f32_e32 v88, 0, v88
	v_max_f32_e32 v89, 0, v89
	v_max_f32_e32 v90, 0, v90
	v_max_f32_e32 v91, 0, v91
	v_mul_f32_e32 v92, v92, v92
	v_mul_f32_e32 v93, v93, v93
	v_mul_f32_e32 v94, v94, v94
	v_mul_f32_e32 v95, v95, v95
	v_mul_f32_e32 v88, v88, v88
	v_mul_f32_e32 v89, v89, v89
	v_mul_f32_e32 v90, v90, v90
	v_mul_f32_e32 v91, v91, v91
	v_cvt_pk_bf16_f32 v92, v92, v93
	v_cvt_pk_bf16_f32 v93, v94, v95
	v_cvt_pk_bf16_f32 v94, v88, v89
	v_cvt_pk_bf16_f32 v95, v90, v91
	s_add_u32 s98, s24, 0x1000
	s_addc_u32 s99, s25, 0
	s_nop 0
	global_store_dwordx4 v166, v[92:95], s[98:99]
	v_max_f32_e32 v84, 0, v84
	v_max_f32_e32 v85, 0, v85
	v_max_f32_e32 v86, 0, v86
	v_max_f32_e32 v87, 0, v87
	v_max_f32_e32 v80, 0, v80
	v_max_f32_e32 v81, 0, v81
	v_max_f32_e32 v82, 0, v82
	v_max_f32_e32 v83, 0, v83
	v_mul_f32_e32 v84, v84, v84
	v_mul_f32_e32 v85, v85, v85
	v_mul_f32_e32 v86, v86, v86
	v_mul_f32_e32 v87, v87, v87
	v_mul_f32_e32 v80, v80, v80
	v_mul_f32_e32 v81, v81, v81
	v_mul_f32_e32 v82, v82, v82
	v_mul_f32_e32 v83, v83, v83
	v_cvt_pk_bf16_f32 v84, v84, v85
	v_cvt_pk_bf16_f32 v85, v86, v87
	v_cvt_pk_bf16_f32 v86, v80, v81
	v_cvt_pk_bf16_f32 v87, v82, v83
	s_add_u32 s98, s24, 0x11000
	s_addc_u32 s99, s25, 0
	s_nop 0
	global_store_dwordx4 v166, v[84:87], s[98:99]
	v_max_f32_e32 v76, 0, v76
	v_max_f32_e32 v77, 0, v77
	v_max_f32_e32 v78, 0, v78
	v_max_f32_e32 v79, 0, v79
	v_max_f32_e32 v72, 0, v72
	v_max_f32_e32 v73, 0, v73
	v_max_f32_e32 v74, 0, v74
	v_max_f32_e32 v75, 0, v75
	v_mul_f32_e32 v76, v76, v76
	v_mul_f32_e32 v77, v77, v77
	v_mul_f32_e32 v78, v78, v78
	v_mul_f32_e32 v79, v79, v79
	v_mul_f32_e32 v72, v72, v72
	v_mul_f32_e32 v73, v73, v73
	v_mul_f32_e32 v74, v74, v74
	v_mul_f32_e32 v75, v75, v75
	v_cvt_pk_bf16_f32 v76, v76, v77
	v_cvt_pk_bf16_f32 v77, v78, v79
	v_cvt_pk_bf16_f32 v78, v72, v73
	v_cvt_pk_bf16_f32 v79, v74, v75
	s_add_u32 s98, s24, 0x1800
	s_addc_u32 s99, s25, 0
	s_nop 0
	global_store_dwordx4 v166, v[76:79], s[98:99]
	v_max_f32_e32 v68, 0, v68
	v_max_f32_e32 v69, 0, v69
	v_max_f32_e32 v70, 0, v70
	v_max_f32_e32 v71, 0, v71
	v_max_f32_e32 v64, 0, v64
	v_max_f32_e32 v65, 0, v65
	v_max_f32_e32 v66, 0, v66
	v_max_f32_e32 v67, 0, v67
	v_mul_f32_e32 v68, v68, v68
	v_mul_f32_e32 v69, v69, v69
	v_mul_f32_e32 v70, v70, v70
	v_mul_f32_e32 v71, v71, v71
	v_mul_f32_e32 v64, v64, v64
	v_mul_f32_e32 v65, v65, v65
	v_mul_f32_e32 v66, v66, v66
	v_mul_f32_e32 v67, v67, v67
	v_cvt_pk_bf16_f32 v68, v68, v69
	v_cvt_pk_bf16_f32 v69, v70, v71
	v_cvt_pk_bf16_f32 v70, v64, v65
	v_cvt_pk_bf16_f32 v71, v66, v67
	s_add_u32 s98, s24, 0x11800
	s_addc_u32 s99, s25, 0
	s_nop 0
	global_store_dwordx4 v166, v[68:71], s[98:99]
	v_max_f32_e32 v60, 0, v60
	v_max_f32_e32 v61, 0, v61
	v_max_f32_e32 v62, 0, v62
	v_max_f32_e32 v63, 0, v63
	v_max_f32_e32 v56, 0, v56
	v_max_f32_e32 v57, 0, v57
	v_max_f32_e32 v58, 0, v58
	v_max_f32_e32 v59, 0, v59
	v_mul_f32_e32 v60, v60, v60
	v_mul_f32_e32 v61, v61, v61
	v_mul_f32_e32 v62, v62, v62
	v_mul_f32_e32 v63, v63, v63
	v_mul_f32_e32 v56, v56, v56
	v_mul_f32_e32 v57, v57, v57
	v_mul_f32_e32 v58, v58, v58
	v_mul_f32_e32 v59, v59, v59
	v_cvt_pk_bf16_f32 v60, v60, v61
	v_cvt_pk_bf16_f32 v61, v62, v63
	v_cvt_pk_bf16_f32 v62, v56, v57
	v_cvt_pk_bf16_f32 v63, v58, v59
	s_add_u32 s98, s24, 0x4000
	s_addc_u32 s99, s25, 0
	s_nop 0
	global_store_dwordx4 v166, v[60:63], s[98:99]
	v_max_f32_e32 v52, 0, v52
	v_max_f32_e32 v53, 0, v53
	v_max_f32_e32 v54, 0, v54
	v_max_f32_e32 v55, 0, v55
	v_max_f32_e32 v48, 0, v48
	v_max_f32_e32 v49, 0, v49
	v_max_f32_e32 v50, 0, v50
	v_max_f32_e32 v51, 0, v51
	v_mul_f32_e32 v52, v52, v52
	v_mul_f32_e32 v53, v53, v53
	v_mul_f32_e32 v54, v54, v54
	v_mul_f32_e32 v55, v55, v55
	v_mul_f32_e32 v48, v48, v48
	v_mul_f32_e32 v49, v49, v49
	v_mul_f32_e32 v50, v50, v50
	v_mul_f32_e32 v51, v51, v51
	v_cvt_pk_bf16_f32 v52, v52, v53
	v_cvt_pk_bf16_f32 v53, v54, v55
	v_cvt_pk_bf16_f32 v54, v48, v49
	v_cvt_pk_bf16_f32 v55, v50, v51
	s_add_u32 s98, s24, 0x14000
	s_addc_u32 s99, s25, 0
	s_nop 0
	global_store_dwordx4 v166, v[52:55], s[98:99]
	v_max_f32_e32 v44, 0, v44
	v_max_f32_e32 v45, 0, v45
	v_max_f32_e32 v46, 0, v46
	v_max_f32_e32 v47, 0, v47
	v_max_f32_e32 v40, 0, v40
	v_max_f32_e32 v41, 0, v41
	v_max_f32_e32 v42, 0, v42
	v_max_f32_e32 v43, 0, v43
	v_mul_f32_e32 v44, v44, v44
	v_mul_f32_e32 v45, v45, v45
	v_mul_f32_e32 v46, v46, v46
	v_mul_f32_e32 v47, v47, v47
	v_mul_f32_e32 v40, v40, v40
	v_mul_f32_e32 v41, v41, v41
	v_mul_f32_e32 v42, v42, v42
	v_mul_f32_e32 v43, v43, v43
	v_cvt_pk_bf16_f32 v44, v44, v45
	v_cvt_pk_bf16_f32 v45, v46, v47
	v_cvt_pk_bf16_f32 v46, v40, v41
	v_cvt_pk_bf16_f32 v47, v42, v43
	s_add_u32 s98, s24, 0x4800
	s_addc_u32 s99, s25, 0
	s_nop 0
	global_store_dwordx4 v166, v[44:47], s[98:99]
	v_max_f32_e32 v36, 0, v36
	v_max_f32_e32 v37, 0, v37
	v_max_f32_e32 v38, 0, v38
	v_max_f32_e32 v39, 0, v39
	v_max_f32_e32 v32, 0, v32
	v_max_f32_e32 v33, 0, v33
	v_max_f32_e32 v34, 0, v34
	v_max_f32_e32 v35, 0, v35
	v_mul_f32_e32 v36, v36, v36
	v_mul_f32_e32 v37, v37, v37
	v_mul_f32_e32 v38, v38, v38
	v_mul_f32_e32 v39, v39, v39
	v_mul_f32_e32 v32, v32, v32
	v_mul_f32_e32 v33, v33, v33
	v_mul_f32_e32 v34, v34, v34
	v_mul_f32_e32 v35, v35, v35
	v_cvt_pk_bf16_f32 v36, v36, v37
	v_cvt_pk_bf16_f32 v37, v38, v39
	v_cvt_pk_bf16_f32 v38, v32, v33
	v_cvt_pk_bf16_f32 v39, v34, v35
	s_add_u32 s98, s24, 0x14800
	s_addc_u32 s99, s25, 0
	s_nop 0
	global_store_dwordx4 v166, v[36:39], s[98:99]
	v_max_f32_e32 v28, 0, v28
	v_max_f32_e32 v29, 0, v29
	v_max_f32_e32 v30, 0, v30
	v_max_f32_e32 v31, 0, v31
	v_max_f32_e32 v24, 0, v24
	v_max_f32_e32 v25, 0, v25
	v_max_f32_e32 v26, 0, v26
	v_max_f32_e32 v27, 0, v27
	v_mul_f32_e32 v28, v28, v28
	v_mul_f32_e32 v29, v29, v29
	v_mul_f32_e32 v30, v30, v30
	v_mul_f32_e32 v31, v31, v31
	v_mul_f32_e32 v24, v24, v24
	v_mul_f32_e32 v25, v25, v25
	v_mul_f32_e32 v26, v26, v26
	v_mul_f32_e32 v27, v27, v27
	v_cvt_pk_bf16_f32 v28, v28, v29
	v_cvt_pk_bf16_f32 v29, v30, v31
	v_cvt_pk_bf16_f32 v30, v24, v25
	v_cvt_pk_bf16_f32 v31, v26, v27
	s_add_u32 s98, s24, 0x5000
	s_addc_u32 s99, s25, 0
	s_nop 0
	global_store_dwordx4 v166, v[28:31], s[98:99]
	v_max_f32_e32 v20, 0, v20
	v_max_f32_e32 v21, 0, v21
	v_max_f32_e32 v22, 0, v22
	v_max_f32_e32 v23, 0, v23
	v_max_f32_e32 v16, 0, v16
	v_max_f32_e32 v17, 0, v17
	v_max_f32_e32 v18, 0, v18
	v_max_f32_e32 v19, 0, v19
	v_mul_f32_e32 v20, v20, v20
	v_mul_f32_e32 v21, v21, v21
	v_mul_f32_e32 v22, v22, v22
	v_mul_f32_e32 v23, v23, v23
	v_mul_f32_e32 v16, v16, v16
	v_mul_f32_e32 v17, v17, v17
	v_mul_f32_e32 v18, v18, v18
	v_mul_f32_e32 v19, v19, v19
	v_cvt_pk_bf16_f32 v20, v20, v21
	v_cvt_pk_bf16_f32 v21, v22, v23
	v_cvt_pk_bf16_f32 v22, v16, v17
	v_cvt_pk_bf16_f32 v23, v18, v19
	s_add_u32 s98, s24, 0x15000
	s_addc_u32 s99, s25, 0
	s_nop 0
	global_store_dwordx4 v166, v[20:23], s[98:99]
	v_max_f32_e32 v12, 0, v12
	v_max_f32_e32 v13, 0, v13
	v_max_f32_e32 v14, 0, v14
	v_max_f32_e32 v15, 0, v15
	v_max_f32_e32 v8, 0, v8
	v_max_f32_e32 v9, 0, v9
	v_max_f32_e32 v10, 0, v10
	v_max_f32_e32 v11, 0, v11
	v_mul_f32_e32 v12, v12, v12
	v_mul_f32_e32 v13, v13, v13
	v_mul_f32_e32 v14, v14, v14
	v_mul_f32_e32 v15, v15, v15
	v_mul_f32_e32 v8, v8, v8
	v_mul_f32_e32 v9, v9, v9
	v_mul_f32_e32 v10, v10, v10
	v_mul_f32_e32 v11, v11, v11
	v_cvt_pk_bf16_f32 v12, v12, v13
	v_cvt_pk_bf16_f32 v13, v14, v15
	v_cvt_pk_bf16_f32 v14, v8, v9
	v_cvt_pk_bf16_f32 v15, v10, v11
	s_add_u32 s98, s24, 0x5800
	s_addc_u32 s99, s25, 0
	s_nop 0
	global_store_dwordx4 v166, v[12:15], s[98:99]
	v_max_f32_e32 v4, 0, v4
	v_max_f32_e32 v5, 0, v5
	v_max_f32_e32 v6, 0, v6
	v_max_f32_e32 v7, 0, v7
	v_max_f32_e32 v0, 0, v0
	v_max_f32_e32 v1, 0, v1
	v_max_f32_e32 v2, 0, v2
	v_max_f32_e32 v3, 0, v3
	v_mul_f32_e32 v4, v4, v4
	v_mul_f32_e32 v5, v5, v5
	v_mul_f32_e32 v6, v6, v6
	v_mul_f32_e32 v7, v7, v7
	v_mul_f32_e32 v0, v0, v0
	v_mul_f32_e32 v1, v1, v1
	v_mul_f32_e32 v2, v2, v2
	v_mul_f32_e32 v3, v3, v3
	v_cvt_pk_bf16_f32 v4, v4, v5
	v_cvt_pk_bf16_f32 v5, v6, v7
	v_cvt_pk_bf16_f32 v6, v0, v1
	v_cvt_pk_bf16_f32 v7, v2, v3
	s_add_u32 s98, s24, 0x15800
	s_addc_u32 s99, s25, 0
	s_nop 0
	global_store_dwordx4 v166, v[4:7], s[98:99]
	s_and_b64 vcc, exec, s[4:5]
	s_mov_b64 s[4:5], -1
	s_cbranch_vccnz .LBB0_497
	s_and_b64 vcc, exec, s[0:1]
	s_cbranch_vccnz .LBB0_496
	s_barrier
	s_branch .LBB0_496
